# v80 stack without the MLA LDS-flag handshake (original per-tile s_barrier in the MLA key loop), to attribute the flags
# baseline (speedup 1.0000x reference)
; template <int DQK, bool MASKED, int MODE, class MF>
; DI void attn_step(const bf16_t* sK, const bf16_t* sVt, const bf16x8 (&qf)[DQK / 16], f32x16& o0, f32x16& o1, float& m, float& l,
;                   float sc, const MF& mf, int lane, f32x16 (&s)[2], float invl, bool lanevalid = true) {
;     ...
;   bf16x8 kf[2][DQK / 16];
; #pragma unroll
;   for (int sub = 0; sub < 2; ++sub)
; #pragma unroll
;     for (int ks = 0; ks < DQK / 16; ++ks) kf[sub][ks] = *(const bf16x8*)(sK + (sub * 32 + pr) * KST + ks * 16 + 8 * h);
;   __builtin_amdgcn_sched_barrier(0);
; #pragma unroll
;   for (int q = 0; q < 16; ++q) { s[0][q] = 0.f; s[1][q] = 0.f; }
; #pragma unroll
;   for (int ks = 0; ks < DQK / 16; ++ks) {
;     s[0] = MFMA(kf[0][ks], qf[ks], s[0]);
;     s[1] = MFMA(kf[1][ks], qf[ks], s[1]);
;   }
;   bf16x8 vf[2][2][2];
;   if (MODE != 1) {
; #pragma unroll
;     for (int sub = 0; sub < 2; ++sub)
; #pragma unroll
;       for (int s2 = 0; s2 < 2; ++s2) {
;         vf[sub][s2][0] = *(const bf16x8*)(sVt + r * 72 + sub * 32 + s2 * 16 + 8 * h);
;         vf[sub][s2][1] = *(const bf16x8*)(sVt + (32 + r) * 72 + sub * 32 + s2 * 16 + 8 * h);
;       }
;     __builtin_amdgcn_sched_barrier(0);
;   }
;   float mxr = -3.0e38f;
; #pragma unroll
;   for (int sub = 0; sub < 2; ++sub)
; #pragma unroll
;     for (int q = 0; q < 16; ++q) {
;       if (MASKED) { const int kk = sub * 32 + 16 * (q >> 3) + 8 * h + (q & 7); s[sub][q] = mf(kk) ? s[sub][q] : -3.0e38f; }
;       if (MODE != 2) mxr = fmaxf(mxr, s[sub][q]);
;     }
;   float alpha = 1.f;
;   if (MODE != 2) {
;     float mx = fmaxf(m, mxr * sc);
;     mx = fmaxf(mx, shx(mx, 32));
;     if (!MASKED) mx = lanevalid ? mx : m;
;     alpha = fexp2(m - mx);
;     m = mx;
;   }
;   const float moff = (!MASKED && !lanevalid) ? 1.0e30f : m;
;   float ps = 0.f;
; #pragma unroll
;   for (int sub = 0; sub < 2; ++sub)
; #pragma unroll
;     for (int q = 0; q < 16; ++q) {
;       float pv = fexp2(__builtin_fmaf(s[sub][q], sc, -moff));
;       if (MASKED && MODE != 0) pv = (s[sub][q] > -1.0e38f) ? pv : 0.f;
;       if (MODE == 2) pv *= invl;
;       s[sub][q] = pv;
;       ps += pv;
;     }
;   if (MODE != 2) {
;     ps += shx(ps, 32);
;     l = l * alpha + ps;
;   }
;   if (MODE == 1) return;
;   if (MODE == 0) {
; #pragma unroll
;     for (int q = 0; q < 16; ++q) { o0[q] *= alpha; o1[q] *= alpha; }
.LBB0_785:
	v_cmp_le_i32_e32 vcc, s14, v163
	s_and_saveexec_b64 s[22:23], vcc
	s_cbranch_execz .LBB0_791
	s_add_i32 s24, s14, 63
	s_mulk_i32 s40, 0x2c00
	v_cmp_le_i32_e32 vcc, s24, v162
	s_lshl_b32 s39, s40, 1
	v_max_f32_e32 v0, v186, v186
	s_and_saveexec_b64 s[24:25], vcc
	s_xor_b64 s[24:25], exec, s[24:25]
	s_cbranch_execz .LBB0_788
	v_lshl_add_u32 v14, s40, 1, v143
	ds_read_b128 v[2:5], v14
	ds_read_b128 v[6:9], v14 offset:32
	ds_read_b128 v[10:13], v14 offset:64
	ds_read_b128 v[116:119], v14 offset:96
	ds_read_b128 v[120:123], v14 offset:128
	ds_read_b128 v[124:127], v14 offset:160
	ds_read_b128 v[48:51], v14 offset:6656
	ds_read_b128 v[128:131], v14 offset:6688
	ds_read_b128 v[132:135], v14 offset:6720
	ds_read_b128 v[188:191], v14 offset:6752
	ds_read_b128 v[194:197], v14 offset:6784
	ds_read_b128 v[198:201], v14 offset:6816
	s_waitcnt lgkmcnt(11)
	v_mfma_f32_32x32x16_bf16 v[64:79], v[2:5], v[100:103], 0
	v_add3_u32 v2, s39, v172, v156
	v_add3_u32 v3, s39, v173, v156
	s_waitcnt lgkmcnt(10)
	v_mfma_f32_32x32x16_bf16 v[64:79], v[6:9], v[80:83], v[64:79]
	s_waitcnt lgkmcnt(5)
	v_mfma_f32_32x32x16_bf16 v[48:63], v[48:51], v[100:103], 0
	v_mfma_f32_32x32x16_bf16 v[64:79], v[10:13], v[84:87], v[64:79]
	s_waitcnt lgkmcnt(4)
	v_mfma_f32_32x32x16_bf16 v[48:63], v[128:131], v[80:83], v[48:63]
	v_mfma_f32_32x32x16_bf16 v[64:79], v[116:119], v[88:91], v[64:79]
	s_waitcnt lgkmcnt(3)
	v_mfma_f32_32x32x16_bf16 v[48:63], v[132:135], v[84:87], v[48:63]
	v_mfma_f32_32x32x16_bf16 v[64:79], v[120:123], v[92:95], v[64:79]
	s_waitcnt lgkmcnt(2)
	v_mfma_f32_32x32x16_bf16 v[48:63], v[188:191], v[88:91], v[48:63]
	v_mfma_f32_32x32x16_bf16 v[64:79], v[124:127], v[96:99], v[64:79]
	ds_read_b128 v[132:135], v2 offset:13312
	ds_read_b128 v[124:127], v2 offset:13344
	ds_read_b128 v[128:131], v3 offset:13312
	ds_read_b128 v[120:123], v3 offset:13344
	ds_read_b128 v[116:119], v2 offset:13376
	ds_read_b128 v[6:9], v2 offset:13408
	ds_read_b128 v[10:13], v3 offset:13376
	ds_read_b128 v[2:5], v3 offset:13408
	s_waitcnt lgkmcnt(9)
	v_mfma_f32_32x32x16_bf16 v[48:63], v[194:197], v[92:95], v[48:63]
	s_waitcnt lgkmcnt(8)
	v_mfma_f32_32x32x16_bf16 v[48:63], v[198:201], v[96:99], v[48:63]
	v_max3_f32 v14, v64, s36, v65
	v_max3_f32 v14, v14, v66, v67
	v_max3_f32 v14, v14, v68, v69
	v_max3_f32 v14, v14, v70, v71
	v_max3_f32 v14, v14, v72, v73
	v_max3_f32 v14, v14, v74, v75
	v_max3_f32 v14, v14, v76, v77
	v_max3_f32 v14, v14, v78, v79
	s_nop 3
	v_max3_f32 v14, v14, v48, v49
	v_max3_f32 v14, v14, v50, v51
	v_max3_f32 v14, v14, v52, v53
	v_max3_f32 v14, v14, v54, v55
	v_max3_f32 v14, v14, v56, v57
	v_max3_f32 v14, v14, v58, v59
	v_max3_f32 v14, v14, v60, v61
	v_max3_f32 v14, v14, v62, v63
	v_mul_f32_e32 v14, 0x3e16c740, v14
	v_cmp_lt_i32_e32 vcc, v183, v184
	v_max_f32_e32 v0, v0, v14
	s_nop 0
	v_cndmask_b32_e32 v14, v182, v183, vcc
	v_lshlrev_b32_e32 v14, 2, v14
	ds_bpermute_b32 v15, v14, v0
	s_waitcnt lgkmcnt(0)
	v_max_f32_e32 v15, v15, v15
	v_max_f32_e32 v15, v0, v15
	v_fma_f32 v0, v64, s37, -v15
	v_fma_f32 v64, v65, s37, -v15
	v_exp_f32_e32 v65, v0
	v_exp_f32_e32 v64, v64
	v_fma_f32 v0, v66, s37, -v15
	v_exp_f32_e32 v66, v0
	v_fma_f32 v67, v67, s37, -v15
	v_exp_f32_e32 v67, v67
	v_fma_f32 v68, v68, s37, -v15
	v_sub_f32_e32 v0, v186, v15
	v_add_f32_e32 v186, 0, v65
	v_exp_f32_e32 v68, v68
	v_fma_f32 v69, v69, s37, -v15
	v_add_f32_e32 v186, v64, v186
	v_exp_f32_e32 v69, v69
	v_fma_f32 v70, v70, s37, -v15
	v_add_f32_e32 v186, v66, v186
	v_exp_f32_e32 v70, v70
	v_fma_f32 v71, v71, s37, -v15
	v_add_f32_e32 v186, v67, v186
	v_exp_f32_e32 v71, v71
	v_fma_f32 v72, v72, s37, -v15
	v_add_f32_e32 v186, v68, v186
	v_exp_f32_e32 v72, v72
	v_fma_f32 v73, v73, s37, -v15
	v_add_f32_e32 v186, v69, v186
	v_exp_f32_e32 v73, v73
	v_fma_f32 v74, v74, s37, -v15
	v_add_f32_e32 v186, v70, v186
	v_exp_f32_e32 v74, v74
	v_fma_f32 v75, v75, s37, -v15
	v_add_f32_e32 v186, v71, v186
	v_exp_f32_e32 v75, v75
	v_fma_f32 v76, v76, s37, -v15
	v_add_f32_e32 v186, v72, v186
	v_exp_f32_e32 v76, v76
	v_fma_f32 v77, v77, s37, -v15
	v_add_f32_e32 v186, v73, v186
	v_exp_f32_e32 v77, v77
	v_fma_f32 v78, v78, s37, -v15
	v_add_f32_e32 v186, v74, v186
	v_exp_f32_e32 v78, v78
	v_fma_f32 v79, v79, s37, -v15
	v_add_f32_e32 v186, v75, v186
	v_exp_f32_e32 v79, v79
	v_fma_f32 v48, v48, s37, -v15
	v_add_f32_e32 v186, v76, v186
	v_exp_f32_e32 v187, v48
	v_fma_f32 v48, v49, s37, -v15
	v_add_f32_e32 v186, v77, v186
	v_exp_f32_e32 v188, v48
	v_fma_f32 v48, v50, s37, -v15
	v_add_f32_e32 v186, v78, v186
	v_exp_f32_e32 v189, v48
	v_fma_f32 v49, v51, s37, -v15
	v_add_f32_e32 v48, v79, v186
	v_exp_f32_e32 v186, v49
	v_fma_f32 v49, v52, s37, -v15
	v_add_f32_e32 v48, v187, v48
	v_exp_f32_e32 v52, v49
	v_fma_f32 v49, v53, s37, -v15
	v_add_f32_e32 v48, v188, v48
	v_exp_f32_e32 v53, v49
	v_fma_f32 v49, v54, s37, -v15
	v_add_f32_e32 v48, v189, v48
	v_exp_f32_e32 v54, v49
	v_add_f32_e32 v48, v186, v48
	v_add_f32_e32 v48, v52, v48
	v_exp_f32_e32 v0, v0
	v_add_f32_e32 v48, v53, v48
	v_add_f32_e32 v190, v54, v48
	v_fma_f32 v48, v55, s37, -v15
	v_exp_f32_e32 v55, v48
	v_fma_f32 v48, v56, s37, -v15
	v_exp_f32_e32 v56, v48
	v_pk_mul_f32 v[46:47], v[46:47], v[0:1] op_sel_hi:[1,0]
	v_pk_mul_f32 v[44:45], v[44:45], v[0:1] op_sel_hi:[1,0]
	v_pk_mul_f32 v[42:43], v[42:43], v[0:1] op_sel_hi:[1,0]
	v_pk_mul_f32 v[40:41], v[40:41], v[0:1] op_sel_hi:[1,0]
	v_pk_mul_f32 v[38:39], v[38:39], v[0:1] op_sel_hi:[1,0]
	v_pk_mul_f32 v[36:37], v[36:37], v[0:1] op_sel_hi:[1,0]
	v_pk_mul_f32 v[34:35], v[34:35], v[0:1] op_sel_hi:[1,0]
	v_pk_mul_f32 v[32:33], v[32:33], v[0:1] op_sel_hi:[1,0]
	v_cvt_pk_bf16_f32 v48, v65, v64
	v_cvt_pk_bf16_f32 v49, v66, v67
; #define MFMA(a, b, c) __builtin_amdgcn_mfma_f32_32x32x16_bf16((a), (b), (c), 0, 0, 0)
; DI unsigned pack2(float a, float b) { f32x2_t v = {a, b}; bf16x2_t r = __builtin_convertvector(v, bf16x2_t); return __builtin_bit_cast(unsigned, r); }
; DI float fexp2(float x) { return __builtin_amdgcn_exp2f(x); }
; DI float shx(float v, int m) { return __shfl_xor(v, m, 64); }
; template <int DQK, bool MASKED, int MODE, class MF>
; DI void attn_step(const bf16_t* sK, const bf16_t* sVt, const bf16x8 (&qf)[DQK / 16], f32x16& o0, f32x16& o1, float& m, float& l,
;                   float sc, const MF& mf, int lane, f32x16 (&s)[2], float invl, bool lanevalid = true) {
;     ...
;       if (MASKED) { const int kk = sub * 32 + 16 * (q >> 3) + 8 * h + (q & 7); s[sub][q] = mf(kk) ? s[sub][q] : -3.0e38f; }
;     ...
; #pragma unroll
;   for (int sub = 0; sub < 2; ++sub)
; #pragma unroll
;     for (int q = 0; q < 16; ++q) {
;       float pv = fexp2(__builtin_fmaf(s[sub][q], sc, -moff));
;       if (MASKED && MODE != 0) pv = (s[sub][q] > -1.0e38f) ? pv : 0.f;
;       if (MODE == 2) pv *= invl;
;       s[sub][q] = pv;
;       ps += pv;
;     }
;   if (MODE != 2) {
;     ps += shx(ps, 32);
;     l = l * alpha + ps;
;   }
;   if (MODE == 1) return;
;   if (MODE == 0) {
; #pragma unroll
;     for (int q = 0; q < 16; ++q) { o0[q] *= alpha; o1[q] *= alpha; }
;   }
; #pragma unroll
;   for (int sub = 0; sub < 2; ++sub)
; #pragma unroll
;     for (int s2 = 0; s2 < 2; ++s2) {
;       union { bf16x8 v; unsigned u[4]; } pb;
; #pragma unroll
;       for (int e = 0; e < 4; ++e) pb.u[e] = pack2(s[sub][8 * s2 + 2 * e], s[sub][8 * s2 + 2 * e + 1]);
;       o0 = MFMA(vf[sub][s2][0], pb.v, o0);
;       o1 = MFMA(vf[sub][s2][1], pb.v, o1);
;     }
	v_cvt_pk_bf16_f32 v50, v68, v69
	v_cvt_pk_bf16_f32 v51, v70, v71
	v_pk_mul_f32 v[30:31], v[30:31], v[0:1] op_sel_hi:[1,0]
	v_pk_mul_f32 v[28:29], v[28:29], v[0:1] op_sel_hi:[1,0]
	v_mfma_f32_32x32x16_bf16 v[32:47], v[132:135], v[48:51], v[32:47]
	v_mul_f32_e64 v26, v26, v0
	v_mul_f32_e64 v27, v27, v0
	v_mul_f32_e64 v24, v24, v0
	v_mul_f32_e64 v25, v25, v0
	v_mul_f32_e64 v22, v22, v0
	v_mul_f32_e64 v23, v23, v0
	v_pk_mul_f32 v[20:21], v[20:21], v[0:1] op_sel_hi:[1,0]
	v_pk_mul_f32 v[18:19], v[18:19], v[0:1] op_sel_hi:[1,0]
	v_pk_mul_f32 v[16:17], v[16:17], v[0:1] op_sel_hi:[1,0]
	v_fma_f32 v57, v57, s37, -v15
	v_exp_f32_e32 v57, v57
	v_mfma_f32_32x32x16_bf16 v[16:31], v[128:131], v[48:51], v[16:31]
	v_add_f32_e32 v48, v55, v190
	v_add_f32_e32 v64, v56, v48
	v_cvt_pk_bf16_f32 v48, v72, v73
	v_cvt_pk_bf16_f32 v49, v74, v75
	v_cvt_pk_bf16_f32 v50, v76, v77
	v_cvt_pk_bf16_f32 v51, v78, v79
	v_fma_f32 v58, v58, s37, -v15
	v_exp_f32_e32 v58, v58
	v_mfma_f32_32x32x16_bf16 v[32:47], v[124:127], v[48:51], v[32:47]
	v_fma_f32 v59, v59, s37, -v15
	v_exp_f32_e32 v59, v59
	v_add_f32_e32 v64, v57, v64
	v_add_f32_e32 v64, v58, v64
	v_add_f32_e32 v64, v59, v64
	v_mfma_f32_32x32x16_bf16 v[16:31], v[120:123], v[48:51], v[16:31]
	v_fma_f32 v48, v60, s37, -v15
	v_exp_f32_e32 v60, v48
	v_cvt_pk_bf16_f32 v48, v187, v188
	v_cvt_pk_bf16_f32 v49, v189, v186
	v_cvt_pk_bf16_f32 v50, v52, v53
	v_cvt_pk_bf16_f32 v51, v54, v55
	v_fma_f32 v53, v61, s37, -v15
	v_exp_f32_e32 v53, v53
	v_mfma_f32_32x32x16_bf16 v[32:47], v[116:119], v[48:51], v[32:47]
	v_fma_f32 v54, v62, s37, -v15
	v_exp_f32_e32 v54, v54
	v_fma_f32 v55, v63, s37, -v15
	v_exp_f32_e32 v55, v55
	v_add_f32_e32 v52, v60, v64
	v_mov_b32_e32 v186, v15
	v_mfma_f32_32x32x16_bf16 v[16:31], v[10:13], v[48:51], v[16:31]
	v_add_f32_e32 v10, v53, v52
	v_add_f32_e32 v10, v54, v10
	v_add_f32_e32 v48, v55, v10
	v_cvt_pk_bf16_f32 v10, v56, v57
	v_cvt_pk_bf16_f32 v11, v58, v59
	v_cvt_pk_bf16_f32 v12, v60, v53
	v_cvt_pk_bf16_f32 v13, v54, v55
	s_nop 1
	v_mfma_f32_32x32x16_bf16 v[32:47], v[6:9], v[10:13], v[32:47]
	s_nop 1
	v_mfma_f32_32x32x16_bf16 v[16:31], v[2:5], v[10:13], v[16:31]
	v_fma_f32 v6, v165, v0, v48
	v_mov_b32_e32 v165, v6
.LBB0_788:
	s_andn2_saveexec_b64 s[24:25], s[24:25]
	s_cbranch_execz .LBB0_790
	v_lshl_add_u32 v14, s40, 1, v176
	ds_read_b128 v[2:5], v14
	ds_read_b128 v[6:9], v14 offset:32
	ds_read_b128 v[10:13], v14 offset:64
	ds_read_b128 v[116:119], v14 offset:96
	ds_read_b128 v[120:123], v14 offset:128
	ds_read_b128 v[124:127], v14 offset:160
	ds_read_b128 v[48:51], v14 offset:6656
	ds_read_b128 v[128:131], v14 offset:6688
	ds_read_b128 v[132:135], v14 offset:6720
	ds_read_b128 v[188:191], v14 offset:6752
	ds_read_b128 v[194:197], v14 offset:6784
	ds_read_b128 v[198:201], v14 offset:6816
	s_waitcnt lgkmcnt(11)
	v_mfma_f32_32x32x16_bf16 v[64:79], v[2:5], v[100:103], 0
	v_lshlrev_b32_e32 v2, 1, v175
	v_add3_u32 v3, s39, v172, v2
	v_add3_u32 v2, s39, v173, v2
	s_waitcnt lgkmcnt(10)
	v_mfma_f32_32x32x16_bf16 v[64:79], v[6:9], v[80:83], v[64:79]
	s_waitcnt lgkmcnt(5)
	v_mfma_f32_32x32x16_bf16 v[48:63], v[48:51], v[100:103], 0
	v_mfma_f32_32x32x16_bf16 v[64:79], v[10:13], v[84:87], v[64:79]
	s_waitcnt lgkmcnt(4)
	v_mfma_f32_32x32x16_bf16 v[48:63], v[128:131], v[80:83], v[48:63]
	v_mfma_f32_32x32x16_bf16 v[64:79], v[116:119], v[88:91], v[64:79]
	s_waitcnt lgkmcnt(3)
	v_mfma_f32_32x32x16_bf16 v[48:63], v[132:135], v[84:87], v[48:63]
	v_mfma_f32_32x32x16_bf16 v[64:79], v[120:123], v[92:95], v[64:79]
	s_waitcnt lgkmcnt(2)
	v_mfma_f32_32x32x16_bf16 v[48:63], v[188:191], v[88:91], v[48:63]
	v_mfma_f32_32x32x16_bf16 v[64:79], v[124:127], v[96:99], v[64:79]
	ds_read_b128 v[132:135], v3 offset:13312
	ds_read_b128 v[124:127], v3 offset:13344
	ds_read_b128 v[128:131], v2 offset:13312
	ds_read_b128 v[120:123], v2 offset:13344
	ds_read_b128 v[116:119], v3 offset:13376
	ds_read_b128 v[6:9], v3 offset:13408
	ds_read_b128 v[10:13], v2 offset:13376
	ds_read_b128 v[2:5], v2 offset:13408
	s_waitcnt lgkmcnt(9)
	v_mfma_f32_32x32x16_bf16 v[48:63], v[194:197], v[92:95], v[48:63]
	s_waitcnt lgkmcnt(8)
	v_mfma_f32_32x32x16_bf16 v[48:63], v[198:201], v[96:99], v[48:63]
	v_add_u32_e32 v14, s14, v175
	v_cmp_le_i32_e32 vcc, v14, v164
	s_nop 1
	v_cndmask_b32_e32 v15, v185, v64, vcc
	v_cmp_lt_i32_e32 vcc, v14, v164
	s_nop 1
	v_cndmask_b32_e32 v64, v185, v65, vcc
	v_add_u32_e32 v65, 2, v14
	v_cmp_le_i32_e32 vcc, v65, v164
	s_nop 1
	v_cndmask_b32_e32 v65, v185, v66, vcc
	v_add_u32_e32 v66, 3, v14
	v_cmp_le_i32_e32 vcc, v66, v164
	s_nop 1
	v_cndmask_b32_e32 v66, v185, v67, vcc
	v_add_u32_e32 v67, 4, v14
	v_cmp_le_i32_e32 vcc, v67, v164
	s_nop 1
	v_cndmask_b32_e32 v67, v185, v68, vcc
	v_add_u32_e32 v68, 5, v14
	v_cmp_le_i32_e32 vcc, v68, v164
	s_nop 1
	v_cndmask_b32_e32 v68, v185, v69, vcc
	v_add_u32_e32 v69, 6, v14
	v_cmp_le_i32_e32 vcc, v69, v164
	s_nop 1
	v_cndmask_b32_e32 v69, v185, v70, vcc
	v_add_u32_e32 v70, s14, v174
	v_or_b32_e32 v187, 7, v70
	v_cmp_le_i32_e32 vcc, v187, v164
	v_add_u32_e32 v187, 16, v14
	s_nop 0
	v_cndmask_b32_e32 v71, v185, v71, vcc
	v_cmp_le_i32_e32 vcc, v187, v164
	v_add_u32_e32 v187, 17, v14
	s_nop 0
	v_cndmask_b32_e32 v72, v185, v72, vcc
	v_cmp_le_i32_e32 vcc, v187, v164
	v_add_u32_e32 v187, 18, v14
	s_nop 0
	v_cndmask_b32_e32 v73, v185, v73, vcc
	v_cmp_le_i32_e32 vcc, v187, v164
	v_add_u32_e32 v187, 19, v14
	s_nop 0
	v_cndmask_b32_e32 v74, v185, v74, vcc
	v_cmp_le_i32_e32 vcc, v187, v164
	v_add_u32_e32 v187, 20, v14
	s_nop 0
	v_cndmask_b32_e32 v75, v185, v75, vcc
	v_cmp_le_i32_e32 vcc, v187, v164
	v_add_u32_e32 v187, 21, v14
	s_nop 0
	v_cndmask_b32_e32 v76, v185, v76, vcc
	v_cmp_le_i32_e32 vcc, v187, v164
; DI float shx(float v, int m) { return __shfl_xor(v, m, 64); }
; template <int DQK, bool MASKED, int MODE, class MF>
; DI void attn_step(const bf16_t* sK, const bf16_t* sVt, const bf16x8 (&qf)[DQK / 16], f32x16& o0, f32x16& o1, float& m, float& l,
;                   float sc, const MF& mf, int lane, f32x16 (&s)[2], float invl, bool lanevalid = true) {
;     ...
; #pragma unroll
;   for (int sub = 0; sub < 2; ++sub)
; #pragma unroll
;     for (int q = 0; q < 16; ++q) {
;       if (MASKED) { const int kk = sub * 32 + 16 * (q >> 3) + 8 * h + (q & 7); s[sub][q] = mf(kk) ? s[sub][q] : -3.0e38f; }
;       if (MODE != 2) mxr = fmaxf(mxr, s[sub][q]);
;     }
;   float alpha = 1.f;
;   if (MODE != 2) {
;     float mx = fmaxf(m, mxr * sc);
;     mx = fmaxf(mx, shx(mx, 32));
	v_add_u32_e32 v187, 22, v14
	s_nop 0
	v_cndmask_b32_e32 v77, v185, v77, vcc
	v_cmp_le_i32_e32 vcc, v187, v164
	v_or_b32_e32 v187, 23, v70
	s_nop 0
	v_cndmask_b32_e32 v78, v185, v78, vcc
	v_cmp_le_i32_e32 vcc, v187, v164
	v_add_u32_e32 v187, 32, v14
	s_nop 0
	v_cndmask_b32_e32 v79, v185, v79, vcc
	v_cmp_le_i32_e32 vcc, v187, v164
	v_add_u32_e32 v187, 33, v14
	s_nop 0
	v_cndmask_b32_e32 v48, v185, v48, vcc
	v_cmp_le_i32_e32 vcc, v187, v164
	v_add_u32_e32 v187, 34, v14
	s_nop 0
	v_cndmask_b32_e32 v49, v185, v49, vcc
	v_cmp_le_i32_e32 vcc, v187, v164
	v_add_u32_e32 v187, 35, v14
	s_nop 0
	v_cndmask_b32_e32 v50, v185, v50, vcc
	v_cmp_le_i32_e32 vcc, v187, v164
	v_add_u32_e32 v187, 36, v14
	s_nop 0
	v_cndmask_b32_e32 v51, v185, v51, vcc
	v_cmp_le_i32_e32 vcc, v187, v164
	v_add_u32_e32 v187, 37, v14
	s_nop 0
	v_cndmask_b32_e32 v52, v185, v52, vcc
	v_cmp_le_i32_e32 vcc, v187, v164
	v_add_u32_e32 v187, 38, v14
	s_nop 0
	v_cndmask_b32_e32 v53, v185, v53, vcc
	v_cmp_le_i32_e32 vcc, v187, v164
	v_or_b32_e32 v187, 39, v70
	s_nop 0
	v_cndmask_b32_e32 v54, v185, v54, vcc
	v_cmp_le_i32_e32 vcc, v187, v164
	v_add_u32_e32 v187, 48, v14
	s_nop 0
	v_cndmask_b32_e32 v55, v185, v55, vcc
	v_cmp_le_i32_e32 vcc, v187, v164
	v_add_u32_e32 v187, 49, v14
	s_nop 0
	v_cndmask_b32_e32 v56, v185, v56, vcc
	v_cmp_le_i32_e32 vcc, v187, v164
	v_add_u32_e32 v187, 50, v14
	s_nop 0
	v_cndmask_b32_e32 v57, v185, v57, vcc
	v_cmp_le_i32_e32 vcc, v187, v164
	v_add_u32_e32 v187, 51, v14
	s_nop 0
	v_cndmask_b32_e32 v58, v185, v58, vcc
	v_cmp_le_i32_e32 vcc, v187, v164
	v_add_u32_e32 v187, 52, v14
	s_nop 0
	v_cndmask_b32_e32 v59, v185, v59, vcc
	v_cmp_le_i32_e32 vcc, v187, v164
	v_add_u32_e32 v187, 53, v14
	v_add_u32_e32 v14, 54, v14
	v_cndmask_b32_e32 v60, v185, v60, vcc
	v_cmp_le_i32_e32 vcc, v187, v164
	s_nop 1
	v_cndmask_b32_e32 v61, v185, v61, vcc
	v_cmp_le_i32_e32 vcc, v14, v164
	s_nop 1
	v_cndmask_b32_e32 v14, v185, v62, vcc
	v_or_b32_e32 v62, 55, v70
	v_cmp_le_i32_e32 vcc, v62, v164
	s_nop 1
	v_cndmask_b32_e32 v62, v185, v63, vcc
	v_max3_f32 v63, v15, s36, v64
	v_max3_f32 v63, v63, v65, v66
	v_max3_f32 v63, v63, v67, v68
	v_max3_f32 v63, v63, v69, v71
	v_max3_f32 v63, v63, v72, v73
	v_max3_f32 v63, v63, v74, v75
	v_max3_f32 v63, v63, v76, v77
	v_max3_f32 v63, v63, v78, v79
	v_max3_f32 v63, v63, v48, v49
	v_max3_f32 v63, v63, v50, v51
	v_max3_f32 v63, v63, v52, v53
	v_max3_f32 v63, v63, v54, v55
	v_max3_f32 v63, v63, v56, v57
	v_max3_f32 v63, v63, v58, v59
	v_max3_f32 v63, v63, v60, v61
	v_max3_f32 v63, v63, v14, v62
	v_mul_f32_e32 v63, 0x3e16c740, v63
	v_cmp_lt_i32_e32 vcc, v183, v184
	v_max_f32_e32 v0, v0, v63
	s_nop 0
	v_cndmask_b32_e32 v63, v182, v183, vcc
	v_lshlrev_b32_e32 v63, 2, v63
	ds_bpermute_b32 v70, v63, v0
	s_waitcnt lgkmcnt(0)
; #define MFMA(a, b, c) __builtin_amdgcn_mfma_f32_32x32x16_bf16((a), (b), (c), 0, 0, 0)
; DI unsigned pack2(float a, float b) { f32x2_t v = {a, b}; bf16x2_t r = __builtin_convertvector(v, bf16x2_t); return __builtin_bit_cast(unsigned, r); }
; DI float fexp2(float x) { return __builtin_amdgcn_exp2f(x); }
; DI float shx(float v, int m) { return __shfl_xor(v, m, 64); }
; template <int DQK, bool MASKED, int MODE, class MF>
; DI void attn_step(const bf16_t* sK, const bf16_t* sVt, const bf16x8 (&qf)[DQK / 16], f32x16& o0, f32x16& o1, float& m, float& l,
;                   float sc, const MF& mf, int lane, f32x16 (&s)[2], float invl, bool lanevalid = true) {
;     ...
;   float alpha = 1.f;
;   if (MODE != 2) {
;     float mx = fmaxf(m, mxr * sc);
;     mx = fmaxf(mx, shx(mx, 32));
;     if (!MASKED) mx = lanevalid ? mx : m;
;     alpha = fexp2(m - mx);
;     m = mx;
;   }
;   const float moff = (!MASKED && !lanevalid) ? 1.0e30f : m;
;   float ps = 0.f;
; #pragma unroll
;   for (int sub = 0; sub < 2; ++sub)
; #pragma unroll
;     for (int q = 0; q < 16; ++q) {
;       float pv = fexp2(__builtin_fmaf(s[sub][q], sc, -moff));
;       if (MASKED && MODE != 0) pv = (s[sub][q] > -1.0e38f) ? pv : 0.f;
;       if (MODE == 2) pv *= invl;
;       s[sub][q] = pv;
;       ps += pv;
;     }
;   if (MODE != 2) {
;     ps += shx(ps, 32);
;     l = l * alpha + ps;
;   }
;   if (MODE == 1) return;
;   if (MODE == 0) {
; #pragma unroll
;     for (int q = 0; q < 16; ++q) { o0[q] *= alpha; o1[q] *= alpha; }
;   }
; #pragma unroll
;   for (int sub = 0; sub < 2; ++sub)
; #pragma unroll
;     for (int s2 = 0; s2 < 2; ++s2) {
;       union { bf16x8 v; unsigned u[4]; } pb;
; #pragma unroll
;       for (int e = 0; e < 4; ++e) pb.u[e] = pack2(s[sub][8 * s2 + 2 * e], s[sub][8 * s2 + 2 * e + 1]);
;       o0 = MFMA(vf[sub][s2][0], pb.v, o0);
;       o1 = MFMA(vf[sub][s2][1], pb.v, o1);
;     }
	v_max_f32_e32 v70, v70, v70
	v_max_f32_e32 v70, v0, v70
	v_fma_f32 v0, v15, s37, -v70
	v_exp_f32_e32 v15, v0
	v_fma_f32 v0, v64, s37, -v70
	v_exp_f32_e32 v64, v0
	v_fma_f32 v0, v65, s37, -v70
	v_exp_f32_e32 v65, v0
	v_fma_f32 v66, v66, s37, -v70
	v_exp_f32_e32 v66, v66
	v_fma_f32 v67, v67, s37, -v70
	v_sub_f32_e32 v0, v186, v70
	v_add_f32_e32 v186, 0, v15
	v_exp_f32_e32 v67, v67
	v_fma_f32 v68, v68, s37, -v70
	v_add_f32_e32 v186, v64, v186
	v_exp_f32_e32 v68, v68
	v_fma_f32 v69, v69, s37, -v70
	v_add_f32_e32 v186, v65, v186
	v_exp_f32_e32 v69, v69
	v_fma_f32 v71, v71, s37, -v70
	v_add_f32_e32 v186, v66, v186
	v_exp_f32_e32 v71, v71
	v_fma_f32 v72, v72, s37, -v70
	v_add_f32_e32 v186, v67, v186
	v_exp_f32_e32 v72, v72
	v_fma_f32 v73, v73, s37, -v70
	v_add_f32_e32 v186, v68, v186
	v_exp_f32_e32 v73, v73
	v_fma_f32 v74, v74, s37, -v70
	v_add_f32_e32 v186, v69, v186
	v_exp_f32_e32 v74, v74
	v_fma_f32 v75, v75, s37, -v70
	v_add_f32_e32 v186, v71, v186
	v_exp_f32_e32 v75, v75
	v_fma_f32 v76, v76, s37, -v70
	v_add_f32_e32 v186, v72, v186
	v_exp_f32_e32 v76, v76
	v_fma_f32 v77, v77, s37, -v70
	v_add_f32_e32 v186, v73, v186
	v_exp_f32_e32 v77, v77
	v_fma_f32 v78, v78, s37, -v70
	v_add_f32_e32 v186, v74, v186
	v_exp_f32_e32 v78, v78
	v_fma_f32 v79, v79, s37, -v70
	v_add_f32_e32 v186, v75, v186
	v_exp_f32_e32 v79, v79
	v_fma_f32 v48, v48, s37, -v70
	v_add_f32_e32 v186, v76, v186
	v_exp_f32_e32 v187, v48
	v_fma_f32 v48, v49, s37, -v70
	v_add_f32_e32 v186, v77, v186
	v_exp_f32_e32 v188, v48
	v_fma_f32 v48, v50, s37, -v70
	v_add_f32_e32 v186, v78, v186
	v_exp_f32_e32 v189, v48
	v_fma_f32 v49, v51, s37, -v70
	v_add_f32_e32 v48, v79, v186
	v_exp_f32_e32 v186, v49
	v_fma_f32 v49, v52, s37, -v70
	v_add_f32_e32 v48, v187, v48
	v_exp_f32_e32 v52, v49
	v_fma_f32 v49, v53, s37, -v70
	v_add_f32_e32 v48, v188, v48
	v_exp_f32_e32 v53, v49
	v_fma_f32 v49, v54, s37, -v70
	v_add_f32_e32 v48, v189, v48
	v_exp_f32_e32 v54, v49
	v_add_f32_e32 v48, v186, v48
	v_add_f32_e32 v48, v52, v48
	v_exp_f32_e32 v0, v0
	v_add_f32_e32 v48, v53, v48
	v_add_f32_e32 v190, v54, v48
	v_fma_f32 v48, v55, s37, -v70
	v_exp_f32_e32 v55, v48
	v_fma_f32 v48, v56, s37, -v70
	v_exp_f32_e32 v56, v48
	v_pk_mul_f32 v[46:47], v[46:47], v[0:1] op_sel_hi:[1,0]
	v_pk_mul_f32 v[44:45], v[44:45], v[0:1] op_sel_hi:[1,0]
	v_pk_mul_f32 v[42:43], v[42:43], v[0:1] op_sel_hi:[1,0]
	v_pk_mul_f32 v[40:41], v[40:41], v[0:1] op_sel_hi:[1,0]
	v_pk_mul_f32 v[38:39], v[38:39], v[0:1] op_sel_hi:[1,0]
	v_pk_mul_f32 v[36:37], v[36:37], v[0:1] op_sel_hi:[1,0]
	v_pk_mul_f32 v[34:35], v[34:35], v[0:1] op_sel_hi:[1,0]
	v_pk_mul_f32 v[32:33], v[32:33], v[0:1] op_sel_hi:[1,0]
	v_pk_mul_f32 v[30:31], v[30:31], v[0:1] op_sel_hi:[1,0]
	v_cvt_pk_bf16_f32 v48, v15, v64
	v_cvt_pk_bf16_f32 v49, v65, v66
	v_cvt_pk_bf16_f32 v50, v67, v68
	v_cvt_pk_bf16_f32 v51, v69, v71
	v_pk_mul_f32 v[28:29], v[28:29], v[0:1] op_sel_hi:[1,0]
	v_pk_mul_f32 v[26:27], v[26:27], v[0:1] op_sel_hi:[1,0]
	v_pk_mul_f32 v[24:25], v[24:25], v[0:1] op_sel_hi:[1,0]
	v_pk_mul_f32 v[22:23], v[22:23], v[0:1] op_sel_hi:[1,0]
	v_pk_mul_f32 v[20:21], v[20:21], v[0:1] op_sel_hi:[1,0]
	v_pk_mul_f32 v[18:19], v[18:19], v[0:1] op_sel_hi:[1,0]
	v_pk_mul_f32 v[16:17], v[16:17], v[0:1] op_sel_hi:[1,0]
	v_mfma_f32_32x32x16_bf16 v[32:47], v[132:135], v[48:51], v[32:47]
	v_fma_f32 v57, v57, s37, -v70
	v_exp_f32_e32 v57, v57
	v_fma_f32 v58, v58, s37, -v70
	v_exp_f32_e32 v58, v58
	v_fma_f32 v59, v59, s37, -v70
	v_add_f32_e32 v15, v55, v190
	v_exp_f32_e32 v59, v59
	v_mfma_f32_32x32x16_bf16 v[16:31], v[128:131], v[48:51], v[16:31]
	v_cvt_pk_bf16_f32 v48, v72, v73
	v_cvt_pk_bf16_f32 v49, v74, v75
	v_cvt_pk_bf16_f32 v50, v76, v77
	v_cvt_pk_bf16_f32 v51, v78, v79
	v_add_f32_e32 v15, v56, v15
	v_add_f32_e32 v15, v57, v15
	v_fma_f32 v14, v14, s37, -v70
	v_mfma_f32_32x32x16_bf16 v[32:47], v[124:127], v[48:51], v[32:47]
	v_add_f32_e32 v15, v58, v15
	v_exp_f32_e32 v14, v14
	v_add_f32_e32 v15, v59, v15
	v_mfma_f32_32x32x16_bf16 v[16:31], v[120:123], v[48:51], v[16:31]
	v_fma_f32 v48, v60, s37, -v70
	v_exp_f32_e32 v60, v48
	v_cvt_pk_bf16_f32 v48, v187, v188
	v_cvt_pk_bf16_f32 v49, v189, v186
	v_cvt_pk_bf16_f32 v50, v52, v53
	v_cvt_pk_bf16_f32 v51, v54, v55
	v_fma_f32 v52, v61, s37, -v70
	v_exp_f32_e32 v52, v52
	v_mfma_f32_32x32x16_bf16 v[32:47], v[116:119], v[48:51], v[32:47]
	v_fma_f32 v53, v62, s37, -v70
	v_exp_f32_e32 v53, v53
	v_add_f32_e32 v15, v60, v15
	v_mov_b32_e32 v186, v70
	v_mfma_f32_32x32x16_bf16 v[16:31], v[10:13], v[48:51], v[16:31]
	v_add_f32_e32 v10, v52, v15
	v_add_f32_e32 v10, v14, v10
	v_add_f32_e32 v15, v53, v10
	v_cvt_pk_bf16_f32 v10, v56, v57
	v_cvt_pk_bf16_f32 v11, v58, v59
	v_cvt_pk_bf16_f32 v12, v60, v52
	v_cvt_pk_bf16_f32 v13, v14, v53
	s_nop 1
	v_mfma_f32_32x32x16_bf16 v[32:47], v[6:9], v[10:13], v[32:47]
	s_nop 1
	v_mfma_f32_32x32x16_bf16 v[16:31], v[2:5], v[10:13], v[16:31]
	v_fma_f32 v6, v165, v0, v15
	v_mov_b32_e32 v165, v6
